# conversion-loop f32 weight loads with default cache policy instead of nt
# baseline (speedup 1.0000x reference)
; __device__ __forceinline__ void tr_item_cu(const float* __restrict__ W, int K, int N, bf16* __restrict__ WT, const float* rowgain, int mode, LAS unsigned char* buf, int item, int wave, int lane) {
;     const int nblk = N >> 7, kb = item / nblk, nb = item - kb * nblk, k0 = 256 * kb, n0 = 128 * nb;
;     const int hr = lane >> 5, c = lane & 31, kw = 32 * wave + 16 * hr;
;     f32x4 v[16];
;     const float* src = W + (size_t)(k0 + kw) * N + n0 + 4 * c;
; #pragma unroll
;     for (int j = 0; j < 16; ++j) v[j] = __builtin_nontemporal_load((const f32x4*)(src + (size_t)j * N));
;     if (rowgain) {
; #pragma unroll
;         for (int q = 0; q < 4; ++q) { const f32x4 r4 = *(const f32x4*)(rowgain + k0 + kw + 4 * q);
; #pragma unroll
;             for (int e = 0; e < 4; ++e) v[4 * q + e] = v[4 * q + e] * r4[e]; }
;     }
.LBB0_55:
	s_lshr_b32 s18, s34, 7
	v_cvt_f32_u32_e32 v2, s18
	s_sub_i32 s26, 0, s18
	s_abs_i32 s23, s47
	s_ashr_i32 s22, s47, 31
	v_rcp_iflag_f32_e32 v2, v2
	s_mov_b32 s35, s19
	v_mul_f32_e32 v2, 0x4f7ffffe, v2
	v_cvt_u32_f32_e32 v2, v2
	s_nop 0
	v_readfirstlane_b32 s27, v2
	s_mul_i32 s26, s26, s27
	s_mul_hi_u32 s26, s27, s26
	s_add_i32 s27, s27, s26
	s_mul_hi_u32 s26, s23, s27
	s_mul_i32 s27, s26, s18
	s_sub_i32 s23, s23, s27
	s_add_i32 s46, s26, 1
	s_sub_i32 s27, s23, s18
	s_cmp_ge_u32 s23, s18
	s_cselect_b32 s26, s46, s26
	s_cselect_b32 s23, s27, s23
	s_add_i32 s27, s26, 1
	s_cmp_ge_u32 s23, s18
	s_cselect_b32 s23, s27, s26
	s_xor_b32 s23, s23, s22
	s_sub_i32 s22, s23, s22
	s_lshl_b32 s26, s22, 8
	s_mul_i32 s18, s22, s18
	v_add_u32_e32 v2, s26, v66
	s_sub_i32 s18, s47, s18
	v_ashrrev_i32_e32 v5, 31, v2
	v_mad_u64_u32 v[2:3], s[46:47], v2, s34, 0
	v_mov_b32_e32 v4, v3
	v_mad_u64_u32 v[4:5], s[46:47], v5, s34, v[4:5]
	s_lshl_b32 s22, s18, 7
	v_mov_b32_e32 v3, v4
	v_lshl_add_u64 v[2:3], v[2:3], 2, s[28:29]
	s_ashr_i32 s23, s22, 31
	v_lshl_add_u64 v[2:3], s[22:23], 2, v[2:3]
	v_lshl_add_u64 v[50:51], v[2:3], 0, v[70:71]
	s_lshl_b32 s18, s34, 1
	v_lshl_add_u64 v[18:19], s[18:19], 2, v[50:51]
	s_mul_i32 s18, s34, 3
	v_lshl_add_u64 v[20:21], s[18:19], 2, v[50:51]
	s_lshl_b32 s18, s34, 2
	v_lshl_add_u64 v[26:27], s[18:19], 2, v[50:51]
	s_mul_i32 s18, s34, 5
	v_lshl_add_u64 v[28:29], s[18:19], 2, v[50:51]
	s_mul_i32 s18, s34, 6
	v_lshl_add_u64 v[34:35], s[18:19], 2, v[50:51]
	s_mul_i32 s18, s34, 7
	v_lshl_add_u64 v[36:37], s[18:19], 2, v[50:51]
	s_lshl_b32 s18, s34, 3
	v_lshl_add_u64 v[42:43], s[18:19], 2, v[50:51]
	s_mul_i32 s18, s34, 9
	v_lshl_add_u64 v[44:45], s[18:19], 2, v[50:51]
	s_mul_i32 s18, s34, 10
	v_lshl_add_u64 v[52:53], s[18:19], 2, v[50:51]
	s_mul_i32 s18, s34, 11
	v_lshl_add_u64 v[54:55], s[18:19], 2, v[50:51]
	s_mul_i32 s18, s34, 12
	v_lshl_add_u64 v[120:121], s[18:19], 2, v[50:51]
	s_mul_i32 s18, s34, 13
	v_lshl_add_u64 v[122:123], s[18:19], 2, v[50:51]
	s_mul_i32 s18, s34, 14
	v_lshl_add_u64 v[10:11], s[34:35], 2, v[50:51]
	v_lshl_add_u64 v[124:125], s[18:19], 2, v[50:51]
	s_mul_i32 s18, s34, 15
	global_load_dwordx4 v[2:5], v[50:51], off
	global_load_dwordx4 v[6:9], v[10:11], off
	s_nop 0
	global_load_dwordx4 v[10:13], v[18:19], off
	global_load_dwordx4 v[14:17], v[20:21], off
	s_nop 0
	global_load_dwordx4 v[18:21], v[26:27], off
	global_load_dwordx4 v[22:25], v[28:29], off
	s_nop 0
	global_load_dwordx4 v[26:29], v[34:35], off
	global_load_dwordx4 v[30:33], v[36:37], off
	s_nop 0
	global_load_dwordx4 v[34:37], v[42:43], off
	global_load_dwordx4 v[38:41], v[44:45], off
	s_nop 0
	global_load_dwordx4 v[42:45], v[52:53], off
	global_load_dwordx4 v[46:49], v[54:55], off
	v_lshl_add_u64 v[126:127], s[18:19], 2, v[50:51]
	global_load_dwordx4 v[58:61], v[120:121], off
	global_load_dwordx4 v[62:65], v[122:123], off
	global_load_dwordx4 v[50:53], v[124:125], off
	global_load_dwordx4 v[54:57], v[126:127], off
	s_ashr_i32 s27, s26, 31
	s_cmp_eq_u64 s[30:31], 0
	s_cbranch_scc1 .LBB0_57
	s_lshl_b64 s[28:29], s[26:27], 2
	s_add_u32 s28, s30, s28
	s_addc_u32 s29, s31, s29
	v_lshl_add_u64 v[132:133], v[66:67], 2, s[28:29]
	global_load_dwordx4 v[120:123], v[132:133], off
	global_load_dwordx4 v[124:127], v[132:133], off offset:16
	global_load_dwordx4 v[128:131], v[132:133], off offset:32
	s_nop 0
	global_load_dwordx4 v[132:135], v[132:133], off offset:48
	s_waitcnt vmcnt(0)
	v_pk_mul_f32 v[4:5], v[4:5], v[120:121] op_sel_hi:[1,0]
	v_pk_mul_f32 v[2:3], v[2:3], v[120:121] op_sel_hi:[1,0]
	v_pk_mul_f32 v[8:9], v[8:9], v[120:121] op_sel:[0,1]
	v_pk_mul_f32 v[6:7], v[6:7], v[120:121] op_sel:[0,1]
	v_pk_mul_f32 v[12:13], v[12:13], v[122:123] op_sel_hi:[1,0]
	v_pk_mul_f32 v[10:11], v[10:11], v[122:123] op_sel_hi:[1,0]
	v_mov_b32_e32 v120, v123
	v_pk_mul_f32 v[20:21], v[20:21], v[124:125] op_sel_hi:[1,0]
	v_pk_mul_f32 v[18:19], v[18:19], v[124:125] op_sel_hi:[1,0]
	v_pk_mul_f32 v[24:25], v[24:25], v[124:125] op_sel:[0,1]
	v_pk_mul_f32 v[22:23], v[22:23], v[124:125] op_sel:[0,1]
	v_pk_mul_f32 v[28:29], v[28:29], v[126:127] op_sel_hi:[1,0]
	v_pk_mul_f32 v[26:27], v[26:27], v[126:127] op_sel_hi:[1,0]
	v_mov_b32_e32 v122, v127
	v_mov_b32_e32 v124, v131
	v_mov_b32_e32 v126, v135
	v_pk_mul_f32 v[36:37], v[36:37], v[128:129] op_sel_hi:[1,0]
	v_pk_mul_f32 v[34:35], v[34:35], v[128:129] op_sel_hi:[1,0]
	v_pk_mul_f32 v[40:41], v[40:41], v[128:129] op_sel:[0,1]
	v_pk_mul_f32 v[38:39], v[38:39], v[128:129] op_sel:[0,1]
	v_pk_mul_f32 v[44:45], v[44:45], v[130:131] op_sel_hi:[1,0]
	v_pk_mul_f32 v[42:43], v[42:43], v[130:131] op_sel_hi:[1,0]
	v_pk_mul_f32 v[60:61], v[60:61], v[132:133] op_sel_hi:[1,0]
	v_pk_mul_f32 v[58:59], v[58:59], v[132:133] op_sel_hi:[1,0]
	v_pk_mul_f32 v[64:65], v[64:65], v[132:133] op_sel:[0,1]
	v_pk_mul_f32 v[62:63], v[62:63], v[132:133] op_sel:[0,1]
	v_pk_mul_f32 v[52:53], v[52:53], v[134:135] op_sel_hi:[1,0]
	v_pk_mul_f32 v[50:51], v[50:51], v[134:135] op_sel_hi:[1,0]
	v_pk_mul_f32 v[16:17], v[16:17], v[120:121] op_sel_hi:[1,0]
	v_pk_mul_f32 v[14:15], v[14:15], v[120:121] op_sel_hi:[1,0]
	v_pk_mul_f32 v[32:33], v[32:33], v[122:123] op_sel_hi:[1,0]
	v_pk_mul_f32 v[30:31], v[30:31], v[122:123] op_sel_hi:[1,0]
	v_pk_mul_f32 v[48:49], v[48:49], v[124:125] op_sel_hi:[1,0]
	v_pk_mul_f32 v[46:47], v[46:47], v[124:125] op_sel_hi:[1,0]
	v_pk_mul_f32 v[56:57], v[56:57], v[126:127] op_sel_hi:[1,0]
	v_pk_mul_f32 v[54:55], v[54:55], v[126:127] op_sel_hi:[1,0]
